# tail conversion rebalanced: CUs with 4 P1 tiles also convert one weight item per wave (1536 items), tail CUs take the rest
# speedup vs baseline: 1.0223x; 1.0062x over previous
.Ltail_mod_done:
	v_readlane_b32 s5, v252, 0
	s_sub_u32 s6, s3, s4
	v_readfirstlane_b32 s7, v194
	s_lshr_b32 s7, s7, 6
	s_lshl_b32 s71, s6, 3
	s_lshl_b32 s9, s4, 3
	s_sub_u32 s9, 0x2520, s9
	s_cmp_lt_u32 s5, s4
	s_cbranch_scc1 .Ltail_main
	s_sub_u32 s5, s5, s4
	s_lshl_b32 s5, s5, 3
	s_add_u32 s70, s5, s7
	s_branch .Ltail_go
.Ltail_main:
	s_lshl_b32 s5, s5, 3
	s_add_u32 s70, s5, s7
	s_add_u32 s70, s70, s9
	s_movk_i32 s9, 0x2520
	s_movk_i32 s71, 0x4000
.Ltail_go:
	s_add_u32 s45, s62, 1
	s_cmp_ge_u32 s70, s9
	s_cbranch_scc1 .Ltail_end
	v_readlane_b32 s64, v252, 15
	v_readlane_b32 s65, v252, 16
	s_mul_i32 s4, s45, 0x3a30000
	s_add_u32 s64, s64, s4
	s_addc_u32 s65, s65, 0
	v_readlane_b32 s66, v252, 27
	v_readlane_b32 s67, v252, 28
	s_mul_i32 s4, s45, 0x1e00000
	s_add_u32 s66, s66, s4
	s_addc_u32 s67, s67, 0
	v_readlane_b32 s68, v252, 13
	v_readlane_b32 s69, v252, 14
	s_lshl_b32 s4, s45, 13
	s_add_u32 s68, s68, s4
	s_addc_u32 s69, s69, 0
	v_readlane_b32 s72, v252, 7
	v_readlane_b32 s73, v252, 8
	s_lshl_b32 s4, s45, 24
	s_add_u32 s72, s72, s4
	s_addc_u32 s73, s73, 0
	v_readlane_b32 s74, v252, 29
	v_readlane_b32 s75, v252, 30
	s_lshl_b32 s4, s45, 23
	s_add_u32 s74, s74, s4
	s_addc_u32 s75, s75, 0
	v_mbcnt_lo_u32_b32 v202, -1, 0
	v_mbcnt_hi_u32_b32 v202, -1, v202
	v_lshrrev_b32_e32 v203, 3, v202
	v_and_b32_e32 v204, 7, v202
	s_lshl_b32 s4, s7, 14
	v_mul_u32_u24_e32 v210, 33, v203
	v_lshl_add_u32 v210, v204, 2, v210
	v_lshl_add_u32 v205, v210, 2, s4
	v_mul_u32_u24_e32 v210, 0x108, v204
	v_add_u32_e32 v210, v210, v203
	v_lshl_add_u32 v206, v210, 2, s4
	v_lshlrev_b32_e32 v207, 2, v203
	s_cmp_lt_u32 s70, 0x1d20
	s_cbranch_scc0 .Ltail_m0_p0
	s_mul_hi_u32 s54, s70, 0x1194539
	s_mul_i32 s4, s54, 0xe9
	s_sub_u32 s55, s70, s4
	s_mov_b32 s46, 1
	s_movk_i32 s78, 0x7460
	s_mov_b64 s[56:57], s[64:65]
	s_mov_b64 s[48:49], s[66:67]
	s_branch .Ltail_cm_p0

.Ltail_nm_p0:
	v_mul_lo_u32 v210, s78, v203
	v_lshl_add_u32 v209, v209, 2, v210
	v_lshl_add_u32 v210, s55, 5, v203
	v_lshlrev_b32_e32 v210, 12, v210
	s_lshl_b32 s4, s54, 7
	v_lshl_add_u32 v210, v204, 4, v210
	v_add_u32_e32 v214, s4, v210
	s_lshl_b32 s4, s54, 8
	s_add_u32 s4, s68, s4
	s_addc_u32 s5, s69, 0
	global_load_dword v96, v207, s[4:5]
	global_load_dword v97, v207, s[4:5] offset:32
	global_load_dword v98, v207, s[4:5] offset:64
	global_load_dword v99, v207, s[4:5] offset:96
	global_load_dword v100, v207, s[4:5] offset:128
	global_load_dword v101, v207, s[4:5] offset:160
	global_load_dword v102, v207, s[4:5] offset:192
	global_load_dword v103, v207, s[4:5] offset:224
	global_load_dwordx4 v[6:9], v209, s[76:77]
	s_add_u32 s76, s76, s79
	s_addc_u32 s77, s77, 0
	global_load_dwordx4 v[10:13], v209, s[76:77]
	s_add_u32 s76, s76, s79
	s_addc_u32 s77, s77, 0
	global_load_dwordx4 v[14:17], v209, s[76:77]
	s_add_u32 s76, s76, s79
	s_addc_u32 s77, s77, 0
	global_load_dwordx4 v[18:21], v209, s[76:77]
	s_add_u32 s76, s76, s79
	s_addc_u32 s77, s77, 0
	global_load_dwordx4 v[22:25], v209, s[76:77]
	s_add_u32 s76, s76, s79
	s_addc_u32 s77, s77, 0
	global_load_dwordx4 v[26:29], v209, s[76:77]
	s_add_u32 s76, s76, s79
	s_addc_u32 s77, s77, 0
	global_load_dwordx4 v[30:33], v209, s[76:77]
	s_add_u32 s76, s76, s79
	s_addc_u32 s77, s77, 0
	global_load_dwordx4 v[34:37], v209, s[76:77]
	s_mov_b32 s52, 0
	s_add_u32 s70, s70, s71
	s_cmp_lt_u32 s70, s9
	s_cbranch_scc0 .Ltail_ni_p1
	s_cmp_lt_u32 s70, 0x1d20
	s_cbranch_scc0 .Ltail_m0_p1
	s_mul_hi_u32 s54, s70, 0x1194539
	s_mul_i32 s4, s54, 0xe9
	s_sub_u32 s55, s70, s4
	s_mov_b32 s47, 1
	s_movk_i32 s78, 0x7460
	s_mov_b64 s[56:57], s[64:65]
	s_mov_b64 s[50:51], s[66:67]
	s_branch .Ltail_cm_p1

.Ltail_ni_p1:
.Ltail_loop:
	s_add_u32 s70, s70, s71
	s_cmp_lt_u32 s70, s9
	s_cbranch_scc0 .Ltail_ni_r0
	s_cmp_lt_u32 s70, 0x1d20
	s_cbranch_scc0 .Ltail_m0_r0
	s_mul_hi_u32 s54, s70, 0x1194539
	s_mul_i32 s4, s54, 0xe9
	s_sub_u32 s55, s70, s4
	s_mov_b32 s58, 1
	s_movk_i32 s78, 0x7460
	s_mov_b64 s[56:57], s[64:65]
	s_mov_b64 s[60:61], s[66:67]
	s_branch .Ltail_cm_r0

.Ltail_gk_A:
	v_mul_f32_e32 v217, v96, v213
	v_mul_f32_e32 v6, v6, v217
	v_mul_f32_e32 v7, v7, v217
	v_mul_f32_e32 v8, v8, v217
	v_mul_f32_e32 v9, v9, v217
	ds_write_b32 v205, v6 offset:0
	ds_write_b32 v205, v7 offset:4
	ds_write_b32 v205, v8 offset:8
	ds_write_b32 v205, v9 offset:12
	v_mul_f32_e32 v217, v97, v213
	v_mul_f32_e32 v10, v10, v217
	v_mul_f32_e32 v11, v11, v217
	v_mul_f32_e32 v12, v12, v217
	v_mul_f32_e32 v13, v13, v217
	ds_write_b32 v205, v10 offset:1056
	ds_write_b32 v205, v11 offset:1060
	ds_write_b32 v205, v12 offset:1064
	ds_write_b32 v205, v13 offset:1068
	v_mul_f32_e32 v217, v98, v213
	v_mul_f32_e32 v14, v14, v217
	v_mul_f32_e32 v15, v15, v217
	v_mul_f32_e32 v16, v16, v217
	v_mul_f32_e32 v17, v17, v217
	ds_write_b32 v205, v14 offset:2112
	ds_write_b32 v205, v15 offset:2116
	ds_write_b32 v205, v16 offset:2120
	ds_write_b32 v205, v17 offset:2124
	v_mul_f32_e32 v217, v99, v213
	v_mul_f32_e32 v18, v18, v217
	v_mul_f32_e32 v19, v19, v217
	v_mul_f32_e32 v20, v20, v217
	v_mul_f32_e32 v21, v21, v217
	ds_write_b32 v205, v18 offset:3168
	ds_write_b32 v205, v19 offset:3172
	ds_write_b32 v205, v20 offset:3176
	ds_write_b32 v205, v21 offset:3180
	v_mul_f32_e32 v217, v100, v213
	v_mul_f32_e32 v22, v22, v217
	v_mul_f32_e32 v23, v23, v217
	v_mul_f32_e32 v24, v24, v217
	v_mul_f32_e32 v25, v25, v217
	ds_write_b32 v205, v22 offset:4224
	ds_write_b32 v205, v23 offset:4228
	ds_write_b32 v205, v24 offset:4232
	ds_write_b32 v205, v25 offset:4236
	v_mul_f32_e32 v217, v101, v213
	v_mul_f32_e32 v26, v26, v217
	v_mul_f32_e32 v27, v27, v217
	v_mul_f32_e32 v28, v28, v217
	v_mul_f32_e32 v29, v29, v217
	ds_write_b32 v205, v26 offset:5280
	ds_write_b32 v205, v27 offset:5284
	ds_write_b32 v205, v28 offset:5288
	ds_write_b32 v205, v29 offset:5292
	v_mul_f32_e32 v217, v102, v213
	v_mul_f32_e32 v30, v30, v217
	v_mul_f32_e32 v31, v31, v217
	v_mul_f32_e32 v32, v32, v217
	v_mul_f32_e32 v33, v33, v217
	ds_write_b32 v205, v30 offset:6336
	ds_write_b32 v205, v31 offset:6340
	ds_write_b32 v205, v32 offset:6344
	ds_write_b32 v205, v33 offset:6348
	v_mul_f32_e32 v217, v103, v213
	v_mul_f32_e32 v34, v34, v217
	v_mul_f32_e32 v35, v35, v217
	v_mul_f32_e32 v36, v36, v217
	v_mul_f32_e32 v37, v37, v217
	ds_write_b32 v205, v34 offset:7392
	ds_write_b32 v205, v35 offset:7396
	ds_write_b32 v205, v36 offset:7400
	ds_write_b32 v205, v37 offset:7404
	s_waitcnt lgkmcnt(0)
	ds_read2_b32 v[144:145], v206 offset0:0 offset1:33
	ds_read2_b32 v[146:147], v206 offset0:66 offset1:99
	ds_read2_b32 v[148:149], v206 offset0:132 offset1:165
	ds_read2_b32 v[150:151], v206 offset0:198 offset1:231
	s_waitcnt lgkmcnt(3)
	v_cvt_pk_bf16_f32 v152, v144, v145
	s_waitcnt lgkmcnt(2)
	v_cvt_pk_bf16_f32 v153, v146, v147
	s_waitcnt lgkmcnt(1)
	v_cvt_pk_bf16_f32 v154, v148, v149
	s_waitcnt lgkmcnt(0)
	v_cvt_pk_bf16_f32 v155, v150, v151
	s_mov_b64 s[6:7], s[48:49]
	global_store_dwordx4 v214, v[152:155], s[6:7] sc1
	ds_read2_b32 v[144:145], v206 offset0:8 offset1:41
	ds_read2_b32 v[146:147], v206 offset0:74 offset1:107
	ds_read2_b32 v[148:149], v206 offset0:140 offset1:173
	ds_read2_b32 v[150:151], v206 offset0:206 offset1:239
	s_waitcnt lgkmcnt(3)
	v_cvt_pk_bf16_f32 v156, v144, v145
	s_waitcnt lgkmcnt(2)
	v_cvt_pk_bf16_f32 v157, v146, v147
	s_waitcnt lgkmcnt(1)
	v_cvt_pk_bf16_f32 v158, v148, v149
	s_waitcnt lgkmcnt(0)
	v_cvt_pk_bf16_f32 v159, v150, v151
	s_add_u32 s6, s6, 0x8000
	s_addc_u32 s7, s7, 0
	global_store_dwordx4 v214, v[156:159], s[6:7] sc1
	ds_read2_b32 v[144:145], v206 offset0:16 offset1:49
	ds_read2_b32 v[146:147], v206 offset0:82 offset1:115
	ds_read2_b32 v[148:149], v206 offset0:148 offset1:181
	ds_read2_b32 v[150:151], v206 offset0:214 offset1:247
	s_waitcnt lgkmcnt(3)
	v_cvt_pk_bf16_f32 v152, v144, v145
	s_waitcnt lgkmcnt(2)
	v_cvt_pk_bf16_f32 v153, v146, v147
	s_waitcnt lgkmcnt(1)
	v_cvt_pk_bf16_f32 v154, v148, v149
	s_waitcnt lgkmcnt(0)
	v_cvt_pk_bf16_f32 v155, v150, v151
	s_add_u32 s6, s6, 0x8000
	s_addc_u32 s7, s7, 0
	global_store_dwordx4 v214, v[152:155], s[6:7] sc1
	ds_read2_b32 v[144:145], v206 offset0:24 offset1:57
	ds_read2_b32 v[146:147], v206 offset0:90 offset1:123
	ds_read2_b32 v[148:149], v206 offset0:156 offset1:189
	ds_read2_b32 v[150:151], v206 offset0:222 offset1:255
	s_waitcnt lgkmcnt(3)
	v_cvt_pk_bf16_f32 v156, v144, v145
	s_waitcnt lgkmcnt(2)
	v_cvt_pk_bf16_f32 v157, v146, v147
	s_waitcnt lgkmcnt(1)
	v_cvt_pk_bf16_f32 v158, v148, v149
	s_waitcnt lgkmcnt(0)
	v_cvt_pk_bf16_f32 v159, v150, v151
	s_add_u32 s6, s6, 0x8000
	s_addc_u32 s7, s7, 0
	global_store_dwordx4 v214, v[156:159], s[6:7] sc1
	s_cmp_eq_u32 s52, 0
	s_cbranch_scc1 .Ltail_end
	s_sub_u32 s52, s52, 1
	s_add_u32 s70, s70, s71
	s_cmp_lt_u32 s70, s9
	s_cbranch_scc0 .Ltail_ni_r1
	s_cmp_lt_u32 s70, 0x1d20
	s_cbranch_scc0 .Ltail_m0_r1
	s_mul_hi_u32 s54, s70, 0x1194539
	s_mul_i32 s4, s54, 0xe9
	s_sub_u32 s55, s70, s4
	s_mov_b32 s46, 1
	s_movk_i32 s78, 0x7460
	s_mov_b64 s[56:57], s[64:65]
	s_mov_b64 s[48:49], s[66:67]
	s_branch .Ltail_cm_r1

.Ltail_gk_B:
	v_mul_f32_e32 v217, v104, v215
	v_mul_f32_e32 v38, v38, v217
	v_mul_f32_e32 v39, v39, v217
	v_mul_f32_e32 v40, v40, v217
	v_mul_f32_e32 v41, v41, v217
	ds_write_b32 v205, v38 offset:0
	ds_write_b32 v205, v39 offset:4
	ds_write_b32 v205, v40 offset:8
	ds_write_b32 v205, v41 offset:12
	v_mul_f32_e32 v217, v105, v215
	v_mul_f32_e32 v42, v42, v217
	v_mul_f32_e32 v43, v43, v217
	v_mul_f32_e32 v44, v44, v217
	v_mul_f32_e32 v45, v45, v217
	ds_write_b32 v205, v42 offset:1056
	ds_write_b32 v205, v43 offset:1060
	ds_write_b32 v205, v44 offset:1064
	ds_write_b32 v205, v45 offset:1068
	v_mul_f32_e32 v217, v106, v215
	v_mul_f32_e32 v46, v46, v217
	v_mul_f32_e32 v47, v47, v217
	v_mul_f32_e32 v48, v48, v217
	v_mul_f32_e32 v49, v49, v217
	ds_write_b32 v205, v46 offset:2112
	ds_write_b32 v205, v47 offset:2116
	ds_write_b32 v205, v48 offset:2120
	ds_write_b32 v205, v49 offset:2124
	v_mul_f32_e32 v217, v107, v215
	v_mul_f32_e32 v58, v58, v217
	v_mul_f32_e32 v59, v59, v217
	v_mul_f32_e32 v60, v60, v217
	v_mul_f32_e32 v61, v61, v217
	ds_write_b32 v205, v58 offset:3168
	ds_write_b32 v205, v59 offset:3172
	ds_write_b32 v205, v60 offset:3176
	ds_write_b32 v205, v61 offset:3180
	v_mul_f32_e32 v217, v108, v215
	v_mul_f32_e32 v62, v62, v217
	v_mul_f32_e32 v63, v63, v217
	v_mul_f32_e32 v64, v64, v217
	v_mul_f32_e32 v65, v65, v217
	ds_write_b32 v205, v62 offset:4224
	ds_write_b32 v205, v63 offset:4228
	ds_write_b32 v205, v64 offset:4232
	ds_write_b32 v205, v65 offset:4236
	v_mul_f32_e32 v217, v109, v215
	v_mul_f32_e32 v66, v66, v217
	v_mul_f32_e32 v67, v67, v217
	v_mul_f32_e32 v68, v68, v217
	v_mul_f32_e32 v69, v69, v217
	ds_write_b32 v205, v66 offset:5280
	ds_write_b32 v205, v67 offset:5284
	ds_write_b32 v205, v68 offset:5288
	ds_write_b32 v205, v69 offset:5292
	v_mul_f32_e32 v217, v110, v215
	v_mul_f32_e32 v88, v88, v217
	v_mul_f32_e32 v89, v89, v217
	v_mul_f32_e32 v90, v90, v217
	v_mul_f32_e32 v91, v91, v217
	ds_write_b32 v205, v88 offset:6336
	ds_write_b32 v205, v89 offset:6340
	ds_write_b32 v205, v90 offset:6344
	ds_write_b32 v205, v91 offset:6348
	v_mul_f32_e32 v217, v111, v215
	v_mul_f32_e32 v92, v92, v217
	v_mul_f32_e32 v93, v93, v217
	v_mul_f32_e32 v94, v94, v217
	v_mul_f32_e32 v95, v95, v217
	ds_write_b32 v205, v92 offset:7392
	ds_write_b32 v205, v93 offset:7396
	ds_write_b32 v205, v94 offset:7400
	ds_write_b32 v205, v95 offset:7404
	s_waitcnt lgkmcnt(0)
	ds_read2_b32 v[144:145], v206 offset0:0 offset1:33
	ds_read2_b32 v[146:147], v206 offset0:66 offset1:99
	ds_read2_b32 v[148:149], v206 offset0:132 offset1:165
	ds_read2_b32 v[150:151], v206 offset0:198 offset1:231
	s_waitcnt lgkmcnt(3)
	v_cvt_pk_bf16_f32 v152, v144, v145
	s_waitcnt lgkmcnt(2)
	v_cvt_pk_bf16_f32 v153, v146, v147
	s_waitcnt lgkmcnt(1)
	v_cvt_pk_bf16_f32 v154, v148, v149
	s_waitcnt lgkmcnt(0)
	v_cvt_pk_bf16_f32 v155, v150, v151
	s_mov_b64 s[6:7], s[50:51]
	global_store_dwordx4 v216, v[152:155], s[6:7] sc1
	ds_read2_b32 v[144:145], v206 offset0:8 offset1:41
	ds_read2_b32 v[146:147], v206 offset0:74 offset1:107
	ds_read2_b32 v[148:149], v206 offset0:140 offset1:173
	ds_read2_b32 v[150:151], v206 offset0:206 offset1:239
	s_waitcnt lgkmcnt(3)
	v_cvt_pk_bf16_f32 v156, v144, v145
	s_waitcnt lgkmcnt(2)
	v_cvt_pk_bf16_f32 v157, v146, v147
	s_waitcnt lgkmcnt(1)
	v_cvt_pk_bf16_f32 v158, v148, v149
	s_waitcnt lgkmcnt(0)
	v_cvt_pk_bf16_f32 v159, v150, v151
	s_add_u32 s6, s6, 0x8000
	s_addc_u32 s7, s7, 0
	global_store_dwordx4 v216, v[156:159], s[6:7] sc1
	ds_read2_b32 v[144:145], v206 offset0:16 offset1:49
	ds_read2_b32 v[146:147], v206 offset0:82 offset1:115
	ds_read2_b32 v[148:149], v206 offset0:148 offset1:181
	ds_read2_b32 v[150:151], v206 offset0:214 offset1:247
	s_waitcnt lgkmcnt(3)
	v_cvt_pk_bf16_f32 v152, v144, v145
	s_waitcnt lgkmcnt(2)
	v_cvt_pk_bf16_f32 v153, v146, v147
	s_waitcnt lgkmcnt(1)
	v_cvt_pk_bf16_f32 v154, v148, v149
	s_waitcnt lgkmcnt(0)
	v_cvt_pk_bf16_f32 v155, v150, v151
	s_add_u32 s6, s6, 0x8000
	s_addc_u32 s7, s7, 0
	global_store_dwordx4 v216, v[152:155], s[6:7] sc1
	ds_read2_b32 v[144:145], v206 offset0:24 offset1:57
	ds_read2_b32 v[146:147], v206 offset0:90 offset1:123
	ds_read2_b32 v[148:149], v206 offset0:156 offset1:189
	ds_read2_b32 v[150:151], v206 offset0:222 offset1:255
	s_waitcnt lgkmcnt(3)
	v_cvt_pk_bf16_f32 v156, v144, v145
	s_waitcnt lgkmcnt(2)
	v_cvt_pk_bf16_f32 v157, v146, v147
	s_waitcnt lgkmcnt(1)
	v_cvt_pk_bf16_f32 v158, v148, v149
	s_waitcnt lgkmcnt(0)
	v_cvt_pk_bf16_f32 v159, v150, v151
	s_add_u32 s6, s6, 0x8000
	s_addc_u32 s7, s7, 0
	global_store_dwordx4 v216, v[156:159], s[6:7] sc1
	s_cmp_eq_u32 s52, 0
	s_cbranch_scc1 .Ltail_end
	s_sub_u32 s52, s52, 1
	s_add_u32 s70, s70, s71
	s_cmp_lt_u32 s70, s9
	s_cbranch_scc0 .Ltail_ni_r2
	s_cmp_lt_u32 s70, 0x1d20
	s_cbranch_scc0 .Ltail_m0_r2
	s_mul_hi_u32 s54, s70, 0x1194539
	s_mul_i32 s4, s54, 0xe9
	s_sub_u32 s55, s70, s4
	s_mov_b32 s47, 1
	s_movk_i32 s78, 0x7460
	s_mov_b64 s[56:57], s[64:65]
	s_mov_b64 s[50:51], s[66:67]
	s_branch .Ltail_cm_r2
